# state-only HGRN pass: removed the four q loads per step, their address math and rotation copies (values were never consumed after the earlier dead-code removal)
# speedup vs baseline: 1.0036x; 1.0036x over previous
; template <bool FULL>
; __device__ __forceinline__ void hgrn_item(LAS unsigned char* lds, const bf16_t* P, bf16_t* AB, int L, int hd, const float* lbv, const float* anorm, const float* S0, const float* Dd, int ns, float* Sout, float* Dout) {
;     ...
;         const size_t roff = (size_t)(16 * n) * N1;
;         {
;             const size_t nro = (size_t)(16 * (n + 1 < nsteps ? n + 1 : n)) * N1;
; #pragma unroll
;             for (int i = 0; i < 4; ++i) { zr[i] = pz[nro + (size_t)i * N1]; qr[i] = pq[nro + (size_t)i * N1]; grn[i] = pg[nro + (size_t)i * N1]; }
;             if (tid < 256) vr = *(const u32x4*)(pv + nro);
;         }
.LBB0_225:
	v_lshl_add_u64 v[74:75], v[42:43], 0, s[2:3]
	s_mov_b32 s4, 0x10c2c000
	v_add_co_u32_e32 v60, vcc, s4, v74
	s_mov_b32 s4, 0x10c2f000
	s_nop 0
	v_addc_co_u32_e32 v61, vcc, 0, v75, vcc
	global_load_ushort v66, v[60:61], off offset:1024
	v_add_co_u32_e32 v60, vcc, s4, v74
	s_nop 0
	v_addc_co_u32_e32 v61, vcc, 0, v75, vcc
	global_load_ushort v64, v[60:61], off
	v_add_co_u32_e32 v60, vcc, 0x10c31000, v74
	s_nop 1
	v_addc_co_u32_e32 v61, vcc, 0, v75, vcc
	v_add_co_u32_e32 v74, vcc, 0x10c34000, v74
	global_load_ushort v63, v[60:61], off offset:3072
	v_addc_co_u32_e32 v75, vcc, 0, v75, vcc
	global_load_ushort v61, v[74:75], off offset:2048
	s_and_saveexec_b64 s[4:5], s[36:37]
	s_cbranch_execz .LBB0_227
	v_lshl_add_u64 v[32:33], v[44:45], 0, s[2:3]
	global_load_dwordx4 v[32:35], v[32:33], off

; template <bool FULL>
; __device__ __forceinline__ void hgrn_item(LAS unsigned char* lds, const bf16_t* P, bf16_t* AB, int L, int hd, const float* lbv, const float* anorm, const float* S0, const float* Dd, int ns, float* Sout, float* Dout) {
;     ...
;         __syncthreads();
;         f32x4 acco = (f32x4){0.f, 0.f, 0.f, 0.f};
;         {
;             const u32x2 vv = *(const LAS u32x2*)(VsT + (16 * w + c16) * 20 + 4 * q4);
;             const bf16x4 vf = __builtin_bit_cast(bf16x4, vv);
;             if (FULL) {
;             bf16x8 qf[4], kf[4];
; #pragma unroll
;             for (int kq = 0; kq < 4; ++kq) {
;                 const u32x2 a0 = *(const LAS u32x2*)(Qt + c16 * 136 + 32 * kq + 4 * q4), a1 = *(const LAS u32x2*)(Qt + c16 * 136 + 32 * kq + 16 + 4 * q4);
;                 const u32x2 b0 = *(const LAS u32x2*)(Kt + c16 * 136 + 32 * kq + 4 * q4), b1 = *(const LAS u32x2*)(Kt + c16 * 136 + 32 * kq + 16 + 4 * q4);
;                 u32x4 qa = (u32x4){a0.x, a0.y, a1.x, a1.y}, ka = (u32x4){b0.x, b0.y, b1.x, b1.y};
;                 qf[kq] = __builtin_bit_cast(bf16x8, qa); kf[kq] = __builtin_bit_cast(bf16x8, ka);
;             }
;             f32x4 accA = (f32x4){0.f, 0.f, 0.f, 0.f};
; #pragma unroll
;             for (int kq = 0; kq < 4; ++kq) accA = __builtin_amdgcn_mfma_f32_16x16x32_bf16(kf[kq], qf[kq], accA, 0, 0, 0);
; #pragma unroll
;             for (int j = 0; j < 4; ++j) accA[j] = (c16 >= 4 * q4 + j) ? accA[j] : 0.f;
;             u32x2 pa; pa.x = cvt_pk_bf16(accA[0], accA[1]); pa.y = cvt_pk_bf16(accA[2], accA[3]);
;             const bf16x4 pA = __builtin_bit_cast(bf16x4, pa);
;             acco = __builtin_amdgcn_mfma_f32_16x16x16bf16_1k(pA, vf, (f32x4){0.f, 0.f, 0.f, 0.f}, 0, 0, 0);
; #pragma unroll
;             for (int kq = 0; kq < 4; ++kq) {
;                 u32x4 sp; sp.x = cvt_pk_bf16(accS[2 * kq][0], accS[2 * kq][1]); sp.y = cvt_pk_bf16(accS[2 * kq][2], accS[2 * kq][3]);
;                 sp.z = cvt_pk_bf16(accS[2 * kq + 1][0], accS[2 * kq + 1][1]); sp.w = cvt_pk_bf16(accS[2 * kq + 1][2], accS[2 * kq + 1][3]);
;                 acco = __builtin_amdgcn_mfma_f32_16x16x32_bf16(qf[kq], __builtin_bit_cast(bf16x8, sp), acco, 0, 0, 0);
;             }
;             }
; #pragma unroll
;             for (int mt = 0; mt < 8; ++mt) {
;                 const u32x2 kh2 = *(const LAS u32x2*)(KhT + (16 * mt + c16) * 20 + 4 * q4);
.LBB0_231:
	s_or_b64 exec, exec, s[4:5]
	v_add_u32_e32 v38, v57, v56
	s_waitcnt lgkmcnt(0)
	s_barrier
	ds_read_b64 v[36:37], v50 offset:13824
	ds_read_b128 v[156:159], v38 offset:18944
	v_add_f32_e32 v48, v48, v46
	v_add_u32_e32 v46, 0x2000, v58
	ds_read2_b64 v[68:71], v46 offset0:64 offset1:144
	v_add_u32_e32 v39, 0x2400, v58
	v_add_u32_e32 v47, 0x2800, v58
	v_add_u32_e32 v67, 0x3000, v58
	ds_read_b128 v[160:163], v38 offset:19008
	ds_read_b128 v[164:167], v38 offset:19072
	ds_read_b128 v[168:171], v38 offset:19136
	ds_read2_b64 v[196:199], v39 offset0:96 offset1:176
	ds_read_b128 v[172:175], v38 offset:19200
	ds_read_b128 v[176:179], v38 offset:19264
	ds_read2_b64 v[200:203], v47 offset0:128 offset1:208
	ds_read_b128 v[180:183], v38 offset:19328
	ds_read_b128 v[184:187], v38 offset:19392
	ds_read2_b64 v[204:207], v67 offset0:32 offset1:112
	s_add_u32 s2, s2, 0x2c000
	s_addc_u32 s3, s3, 0
	s_cmp_eq_u32 s2, 0x554000
	s_waitcnt lgkmcnt(11)
	v_pk_mul_f32 v[28:29], v[28:29], v[156:157]
	v_pk_mul_f32 v[30:31], v[30:31], v[158:159]
	s_waitcnt lgkmcnt(9)
	v_pk_mul_f32 v[24:25], v[24:25], v[160:161]
	v_pk_mul_f32 v[26:27], v[26:27], v[162:163]
	v_mfma_f32_16x16x16_bf16 v[28:31], v[68:69], v[36:37], v[28:31]
	s_nop 0
	v_mfma_f32_16x16x16_bf16 v[24:27], v[70:71], v[36:37], v[24:27]
	s_waitcnt lgkmcnt(6)
	v_pk_mul_f32 v[20:21], v[20:21], v[164:165]
	v_pk_mul_f32 v[22:23], v[22:23], v[166:167]
	v_pk_mul_f32 v[16:17], v[16:17], v[168:169]
	v_pk_mul_f32 v[18:19], v[18:19], v[170:171]
	v_mfma_f32_16x16x16_bf16 v[20:23], v[196:197], v[36:37], v[20:23]
	s_nop 0
	v_mfma_f32_16x16x16_bf16 v[16:19], v[198:199], v[36:37], v[16:19]
	s_waitcnt lgkmcnt(3)
	v_pk_mul_f32 v[12:13], v[12:13], v[172:173]
	v_pk_mul_f32 v[14:15], v[14:15], v[174:175]
	v_pk_mul_f32 v[8:9], v[8:9], v[176:177]
	v_pk_mul_f32 v[10:11], v[10:11], v[178:179]
	v_mfma_f32_16x16x16_bf16 v[12:15], v[200:201], v[36:37], v[12:15]
	s_nop 0
	v_mfma_f32_16x16x16_bf16 v[8:11], v[202:203], v[36:37], v[8:11]
	s_waitcnt lgkmcnt(0)
	v_pk_mul_f32 v[4:5], v[4:5], v[180:181]
	v_pk_mul_f32 v[6:7], v[6:7], v[182:183]
	v_pk_mul_f32 v[0:1], v[0:1], v[184:185]
	v_pk_mul_f32 v[2:3], v[2:3], v[186:187]
	v_mfma_f32_16x16x16_bf16 v[4:7], v[204:205], v[36:37], v[4:7]
	s_nop 0
	v_mfma_f32_16x16x16_bf16 v[0:3], v[206:207], v[36:37], v[0:3]
	s_cbranch_scc1 .LBB0_233
	s_waitcnt vmcnt(0)
	v_mov_b64_e32 v[38:39], v[34:35]
	v_mov_b32_e32 v47, v61
	v_mov_b32_e32 v68, v63
	v_mov_b32_e32 v70, v64
	v_mov_b32_e32 v72, v66
	v_mov_b64_e32 v[36:37], v[32:33]
	s_branch .LBB0_225
; #define LAS __attribute__((address_space(3)))
; __device__ __forceinline__ unsigned cvt_pk_bf16(float lo, float hi) { unsigned r; asm volatile("v_cvt_pk_bf16_f32 %0, %1, %2" : "=v"(r) : "v"(lo), "v"(hi)); return r; }
; __device__ __forceinline__ float bf2f(unsigned short b) { return __uint_as_float(((unsigned)b) << 16); }
; template <bool FULL>
; __device__ __forceinline__ void hgrn_item(LAS unsigned char* lds, const bf16_t* P, bf16_t* AB, int L, int hd, const float* lbv, const float* anorm, const float* S0, const float* Dd, int ns, float* Sout, float* Dout) {
;     ...
;         float cs[4], kk[4], qv[4];
;         {
;             float run = 0.f;
; #pragma unroll
;             for (int i = 0; i < 4; ++i) { float z = bf2f(zc[i]); z = fminf(fmaxf(z, -30.f), 30.f); const float e = __expf(-z), sg = __builtin_amdgcn_rcpf(1.f + e), sn = e * sg;
;                 const float f = lb + oml * sg; run += __builtin_amdgcn_logf(f) * 0.69314718056f; cs[i] = run; kk[i] = oml * sn; qv[i] = bf2f(qc[i]); }
;             qsum[tq * 128 + k] = run;
;         }
;         __syncthreads();
;         {
;             float pre = 0.f, tot = 0.f;
; #pragma unroll
;             for (int j = 0; j < 4; ++j) { const float v = qsum[j * 128 + k]; tot += v; pre += (j < tq) ? v : 0.f; }
;             btot += tot;
;             float kh[4];
; #pragma unroll
;             for (int i = 0; i < 4; ++i) { const float b = pre + cs[i]; const float qt = qv[i] * __expf(b), kt = kk[i] * __expf(fminf(-b, 80.f)); kh[i] = kk[i] * __expf(tot - b);
;                 Qt[(4 * tq + i) * 136 + k] = (bf16_t)(cvt_pk_bf16(qt, 0.f) & 0xffffu); Kt[(4 * tq + i) * 136 + k] = (bf16_t)(cvt_pk_bf16(kt, 0.f) & 0xffffu); }
;             u32x2 kp; kp.x = cvt_pk_bf16(kh[0], kh[1]); kp.y = cvt_pk_bf16(kh[2], kh[3]);
;             *(LAS u32x2*)(KhT + k * 20 + 4 * tq) = kp;
;             if (tq == 0) dvec[k] = __expf(tot);
.LBB0_233:
	v_mul_f32_e32 v48, 0x3f317218, v48
	s_waitcnt vmcnt(0)
	v_lshlrev_b32_e32 v36, 16, v66
	v_max_f32_e32 v36, v36, v36
	v_med3_f32 v36, v36, s29, v225
	v_mul_f32_e32 v36, 0xbfb8aa3b, v36
	v_exp_f32_e32 v36, v36
	s_waitcnt vmcnt(6)
	v_lshlrev_b32_e32 v57, 16, v65
	s_waitcnt vmcnt(4)
	v_lshlrev_b32_e32 v62, 16, v62
	s_waitcnt vmcnt(2)
	v_lshlrev_b32_e32 v60, 16, v60
	v_add_f32_e32 v37, 1.0, v36
	v_rcp_f32_e32 v37, v37
	s_nop 0
	v_mul_f32_e32 v36, v36, v37
	v_mul_f32_e32 v56, v55, v36
	v_lshlrev_b32_e32 v36, 16, v64
	v_max_f32_e32 v36, v36, v36
	v_med3_f32 v36, v36, s29, v225
	v_fma_f32 v37, v55, v37, v53
	v_mul_f32_e32 v36, 0xbfb8aa3b, v36
	v_log_f32_e32 v37, v37
	v_exp_f32_e32 v36, v36
	v_fma_f32 v44, v37, s30, 0
	v_add_f32_e32 v37, 1.0, v36
	v_rcp_f32_e32 v37, v37
	s_nop 0
	v_mul_f32_e32 v36, v36, v37
	v_mul_f32_e32 v64, v55, v36
	v_lshlrev_b32_e32 v36, 16, v63
	v_max_f32_e32 v36, v36, v36
	v_med3_f32 v36, v36, s29, v225
	v_fma_f32 v37, v55, v37, v53
	v_mul_f32_e32 v36, 0xbfb8aa3b, v36
	v_log_f32_e32 v37, v37
	v_exp_f32_e32 v36, v36
	v_fmamk_f32 v58, v37, 0x3f317218, v44
	v_add_f32_e32 v37, 1.0, v36
	v_rcp_f32_e32 v37, v37
	s_nop 0
	v_mul_f32_e32 v36, v36, v37
	v_mul_f32_e32 v63, v55, v36
	s_waitcnt vmcnt(1)
	v_lshlrev_b32_e32 v36, 16, v61
	v_max_f32_e32 v36, v36, v36
	v_med3_f32 v36, v36, s29, v225
	v_mul_f32_e32 v36, 0xbfb8aa3b, v36
	v_exp_f32_e32 v36, v36
	v_fma_f32 v37, v55, v37, v53
	v_log_f32_e32 v37, v37
	v_add_f32_e32 v42, 1.0, v36
	v_rcp_f32_e32 v42, v42
	v_fmamk_f32 v37, v37, 0x3f317218, v58
	v_fmac_f32_e32 v53, v55, v42
	v_mul_f32_e32 v36, v36, v42
	v_log_f32_e32 v42, v53
	v_mul_f32_e32 v53, v55, v36
	s_waitcnt vmcnt(0)
	v_lshlrev_b32_e32 v55, 16, v59
	v_fmamk_f32 v59, v42, 0x3f317218, v37
	ds_write_b32 v54, v59 offset:19456
	s_waitcnt lgkmcnt(0)
	s_barrier
	ds_read2st64_b32 v[42:43], v49 offset0:76 offset1:78
	s_waitcnt lgkmcnt(0)
	v_add_f32_e32 v36, 0, v42
	v_cndmask_b32_e64 v42, 0, v36, s[46:47]
	v_add_f32_e32 v36, v36, v43
	v_cndmask_b32_e64 v43, 0, v43, s[44:45]
	v_add_f32_e32 v45, v42, v43
	ds_read2st64_b32 v[42:43], v49 offset0:80 offset1:82
	s_waitcnt lgkmcnt(0)
	v_add_f32_e32 v36, v36, v42
	v_cndmask_b32_e64 v42, 0, v42, s[42:43]
	v_add_f32_e32 v42, v45, v42
	v_cndmask_b32_e64 v45, 0, v43, s[40:41]
	v_add_f32_e32 v45, v42, v45
	v_add_f32_e32 v42, v44, v45
	v_mul_f32_e32 v44, 0x3fb8aa3b, v42
	v_exp_f32_e32 v44, v44
	s_nop 0
	v_mul_f32_e32 v54, v44, v57
	v_min_f32_e64 v44, -v42, s31
	v_mul_f32_e32 v44, 0x3fb8aa3b, v44
	v_exp_f32_e32 v44, v44
	s_nop 0
	v_mul_f32_e32 v57, v56, v44
	v_mov_b32_e32 v44, v43
	v_cvt_pk_bf16_f32 v43, v54, v195
	ds_write_b16 v51, v43
	v_cvt_pk_bf16_f32 v43, v57, v195
	ds_write_b16 v51, v43 offset:4352
	v_add_f32_e32 v43, v58, v45
	v_pk_add_f32 v[36:37], v[36:37], v[44:45]
	v_mul_f32_e32 v44, 0x3fb8aa3b, v43
	v_exp_f32_e32 v44, v44
	v_min_f32_e64 v54, -v43, s31
	v_mul_f32_e32 v54, 0x3fb8aa3b, v54
	v_exp_f32_e32 v54, v54
	v_mul_f32_e32 v44, v44, v62
	v_cvt_pk_bf16_f32 v44, v44, v195
	ds_write_b16 v51, v44 offset:272
	v_mul_f32_e32 v54, v64, v54
	v_cvt_pk_bf16_f32 v44, v54, v195
	ds_write_b16 v51, v44 offset:4624
	v_mul_f32_e32 v44, 0x3fb8aa3b, v37
	v_exp_f32_e32 v44, v44
	v_min_f32_e64 v54, -v37, s31
	v_mul_f32_e32 v54, 0x3fb8aa3b, v54
	v_exp_f32_e32 v54, v54
	v_mul_f32_e32 v44, v44, v60
	v_cvt_pk_bf16_f32 v44, v44, v195
	ds_write_b16 v51, v44 offset:544
	v_mul_f32_e32 v54, v63, v54
	v_cvt_pk_bf16_f32 v44, v54, v195
	ds_write_b16 v51, v44 offset:4896
	v_add_f32_e32 v44, v59, v45
	v_sub_f32_e32 v42, v36, v42
	v_sub_f32_e32 v43, v36, v43
	v_mul_f32_e32 v45, 0x3fb8aa3b, v44
	v_mul_f32_e32 v42, 0x3fb8aa3b, v42
	v_mul_f32_e32 v43, 0x3fb8aa3b, v43
	v_sub_f32_e32 v37, v36, v37
	v_exp_f32_e32 v45, v45
	v_min_f32_e64 v54, -v44, s31
	v_sub_f32_e32 v44, v36, v44
	v_exp_f32_e32 v42, v42
	v_exp_f32_e32 v43, v43
	v_mul_f32_e32 v37, 0x3fb8aa3b, v37
	v_mul_f32_e32 v54, 0x3fb8aa3b, v54
	v_mul_f32_e32 v44, 0x3fb8aa3b, v44
	v_exp_f32_e32 v37, v37
	v_exp_f32_e32 v54, v54
	v_exp_f32_e32 v44, v44
	v_mul_f32_e32 v45, v45, v55
	v_mul_f32_e32 v42, v56, v42
	v_mul_f32_e32 v43, v64, v43
	v_cvt_pk_bf16_f32 v45, v45, v195
	v_mul_f32_e32 v37, v63, v37
	v_mul_f32_e32 v54, v53, v54
	v_mul_f32_e32 v44, v53, v44
	ds_write_b16 v51, v45 offset:816
	v_cvt_pk_bf16_f32 v45, v54, v195
	ds_write_b16 v51, v45 offset:5168
	v_cvt_pk_bf16_f32 v42, v42, v43
	v_cvt_pk_bf16_f32 v43, v37, v44
	ds_write_b64 v52, v[42:43] offset:8704
	s_and_saveexec_b64 s[2:3], s[38:39]
	s_cbranch_execz .LBB0_235
	v_mul_f32_e32 v37, 0x3fb8aa3b, v36
	v_exp_f32_e32 v37, v37
	ds_write_b32 v49, v37 offset:18944
